# v22 + non-temporal (nt) hint on read-once streams: f32 weight loads, f32 x loads, and the final loop's XN / row-sum loads
# speedup vs baseline: 1.0093x; 1.0093x over previous
; #define LAS __attribute__((address_space(3)))
; #define LDS_WAIT() asm volatile("s_waitcnt lgkmcnt(0)" ::: "memory")
; __device__ __forceinline__ unsigned pk2(float lo, float hi) { return f2bf(lo) | (f2bf(hi) << 16); }
; __device__ __forceinline__ void tr_item(const float* W, int K, int N, const float* kscale, bf16* WT, int dst_row0, LAS float* scr, int k0, int n0, int lane) {
;     const int n4 = 4 * (lane & 7); const bool ok = (n0 + n4) < N;
; #pragma unroll
;     for (int i = 0; i < 8; ++i) { const int kk = 8 * i + (lane >> 3); f32x4 v = ok ? *(const f32x4*)(W + (size_t)(k0 + kk) * N + n0 + n4) : (f32x4){0.f, 0.f, 0.f, 0.f}; if (kscale) v = v * kscale[k0 + kk];
;         scr[kk * 33 + n4] = v[0]; scr[kk * 33 + n4 + 1] = v[1]; scr[kk * 33 + n4 + 2] = v[2]; scr[kk * 33 + n4 + 3] = v[3]; }
;     LDS_WAIT(); asm volatile("" ::: "memory");
;     const int c = lane & 7;
; #pragma unroll
;     for (int j = 0; j < 4; ++j) { const int n = (lane >> 3) + 8 * j; const LAS float* s = scr + (8 * c) * 33 + n;
;         u32x4 o; o.x = pk2(s[0 * 33], s[1 * 33]); o.y = pk2(s[2 * 33], s[3 * 33]); o.z = pk2(s[4 * 33], s[5 * 33]); o.w = pk2(s[6 * 33], s[7 * 33]);
;         *(u32x4*)(WT + (size_t)(dst_row0 + n) * K + k0 + 8 * c) = o; }
;     LDS_WAIT(); asm volatile("" ::: "memory");
; __device__ __forceinline__ void prologue(const Args& a, LAS unsigned char* lds, int wave, int lane) {
;     ...
;         r -= I_WIN;
;         {
;             const float* W = a.in[12] + (size_t)l * D * D;
;             const int nblk = D / 32, kb = r / nblk, nb = r % nblk;
;             tr_item(W, D, D, nullptr, (bf16*)(wl + WOUT_OFF), 32 * nb, scr, 64 * kb, 32 * nb, lane);
;         }
.LBB0_16:
	s_mul_hi_i32 s0, s83, 0x1948b0fd
	s_lshr_b32 s2, s0, 31
	s_ashr_i32 s0, s0, 10
	s_add_i32 s68, s0, s2
	s_mul_i32 s87, s68, 0xffffd780
	s_add_i32 s86, s83, s87
	s_ashr_i32 s69, s68, 31
	s_mul_i32 s2, s68, 0x2880000
	s_mul_hi_i32 s0, s68, 0x2880000
	s_add_u32 s84, s30, s2
	s_addc_u32 s85, s31, s0
	s_cmpk_gt_i32 s86, 0x15ff
	s_mov_b64 s[2:3], -1
	s_cbranch_scc0 .LBB0_58
	s_cmpk_gt_u32 s86, 0x20ff
	s_cbranch_scc0 .LBB0_55
	s_cmpk_gt_u32 s86, 0x267f
	s_cbranch_scc0 .LBB0_20
	s_lshl_b64 s[2:3], s[68:69], 22
	s_add_u32 s4, s20, s2
	s_mul_i32 s0, s68, 0xffffaf00
	s_addc_u32 s3, s21, s3
	s_add_i32 s0, s74, s0
	s_and_b32 s2, s76, 0x3e0
	s_and_b32 s0, s0, 0x7fffffc0
	s_addk_i32 s0, 0xb300
	s_lshl_b32 s5, s2, 2
	s_add_u32 s4, s4, s5
	s_addc_u32 s5, s3, 0
	v_or_b32_e32 v2, s0, v12
	v_mov_b32_e32 v3, v15
	v_or_b32_e32 v4, s0, v1
	v_mov_b32_e32 v5, v15
	v_or_b32_e32 v42, s0, v11
	v_mov_b32_e32 v43, v15
	v_or_b32_e32 v44, s0, v20
	v_mov_b32_e32 v45, v15
	v_or_b32_e32 v50, s0, v21
	v_mov_b32_e32 v51, v15
	v_or_b32_e32 v52, s0, v22
	v_mov_b32_e32 v53, v15
	v_lshl_add_u64 v[18:19], s[4:5], 0, v[14:15]
	v_lshlrev_b64 v[2:3], 12, v[2:3]
	v_lshlrev_b64 v[4:5], 12, v[4:5]
	v_lshlrev_b64 v[42:43], 12, v[42:43]
	v_lshlrev_b64 v[44:45], 12, v[44:45]
	v_lshlrev_b64 v[50:51], 12, v[50:51]
	v_lshlrev_b64 v[52:53], 12, v[52:53]
	v_lshl_add_u64 v[2:3], v[18:19], 0, v[2:3]
	v_lshl_add_u64 v[6:7], v[18:19], 0, v[4:5]
	v_lshl_add_u64 v[42:43], v[18:19], 0, v[42:43]
	v_lshl_add_u64 v[46:47], v[18:19], 0, v[44:45]
	v_lshl_add_u64 v[50:51], v[18:19], 0, v[50:51]
	v_lshl_add_u64 v[54:55], v[18:19], 0, v[52:53]
	global_load_dwordx4 v[2:5], v[2:3], off nt
	s_nop 0
	global_load_dwordx4 v[6:9], v[6:7], off nt
	s_nop 0
	global_load_dwordx4 v[42:45], v[42:43], off nt
	s_nop 0
	global_load_dwordx4 v[46:49], v[46:47], off nt
	s_nop 0
	global_load_dwordx4 v[50:53], v[50:51], off nt
	s_nop 0
	global_load_dwordx4 v[54:57], v[54:55], off nt
	v_or_b32_e32 v58, s0, v23
	v_mov_b32_e32 v59, v15
	v_lshlrev_b64 v[58:59], 12, v[58:59]
	v_lshl_add_u64 v[58:59], v[18:19], 0, v[58:59]
	v_or_b32_e32 v62, s0, v24
	v_mov_b32_e32 v63, v15
	global_load_dwordx4 v[58:61], v[58:59], off nt
	v_lshlrev_b64 v[62:63], 12, v[62:63]
	v_lshl_add_u64 v[18:19], v[18:19], 0, v[62:63]
	global_load_dwordx4 v[62:65], v[18:19], off nt
	s_lshl_b64 s[70:71], s[0:1], 1
	s_add_u32 s70, s84, s70
	v_mov_b32_e32 v17, v15
	s_addc_u32 s71, s85, s71
	v_lshl_add_u64 v[18:19], s[70:71], 0, v[16:17]
	s_mov_b64 s[4:5], 0x1600000
	v_lshl_add_u64 v[18:19], v[18:19], 0, s[4:5]
	s_waitcnt vmcnt(7)
	ds_write2_b32 v26, v2, v3 offset1:1
	ds_write2_b32 v26, v4, v5 offset0:2 offset1:3
	s_waitcnt vmcnt(6)
	ds_write2_b32 v27, v6, v7 offset1:1
	ds_write2_b32 v28, v8, v9 offset1:1
	s_waitcnt vmcnt(5)
	ds_write2_b32 v29, v42, v43 offset1:1
	ds_write2_b32 v30, v44, v45 offset1:1
	s_waitcnt vmcnt(4)
	ds_write2_b32 v31, v46, v47 offset1:1
	ds_write2_b32 v32, v48, v49 offset1:1
	s_waitcnt vmcnt(3)
	ds_write2_b32 v33, v50, v51 offset1:1
	ds_write2_b32 v34, v52, v53 offset1:1
	s_waitcnt vmcnt(2)
	ds_write2_b32 v35, v54, v55 offset1:1
	ds_write2_b32 v36, v56, v57 offset1:1
	s_waitcnt vmcnt(1)
	ds_write2_b32 v37, v58, v59 offset1:1
	ds_write2_b32 v38, v60, v61 offset1:1
	s_waitcnt vmcnt(0)
	ds_write2_b32 v39, v62, v63 offset1:1
	ds_write2_b32 v40, v64, v65 offset1:1
	s_waitcnt lgkmcnt(0)
	ds_read2_b32 v[6:7], v25 offset0:33 offset1:41
	ds_read2_b32 v[8:9], v25 offset1:8
	ds_read2_b32 v[42:43], v25 offset0:66 offset1:74
	ds_read2_b32 v[44:45], v25 offset0:99 offset1:107
	ds_read2_b32 v[46:47], v25 offset0:132 offset1:140
	ds_read2_b32 v[48:49], v25 offset0:165 offset1:173
	ds_read2_b32 v[50:51], v25 offset0:198 offset1:206
	ds_read2_b32 v[52:53], v25 offset0:231 offset1:239
	s_waitcnt lgkmcnt(6)
	v_bfe_u32 v2, v8, 16, 1
	s_waitcnt lgkmcnt(5)
	v_bfe_u32 v4, v42, 16, 1
	v_bfe_u32 v3, v6, 16, 1
	s_waitcnt lgkmcnt(4)
	v_bfe_u32 v5, v44, 16, 1
	s_waitcnt lgkmcnt(3)
	v_bfe_u32 v17, v46, 16, 1
	v_add3_u32 v2, v8, v2, s78
	v_add3_u32 v4, v42, v4, s78
	s_waitcnt lgkmcnt(2)
	v_bfe_u32 v41, v48, 16, 1
	v_add3_u32 v3, v6, v3, s78
	v_add3_u32 v5, v44, v5, s78
	v_add3_u32 v6, v46, v17, s78
	v_lshrrev_b32_e32 v2, 16, v2
	v_lshrrev_b32_e32 v4, 16, v4
	v_add3_u32 v8, v48, v41, s78
	v_lshrrev_b32_e32 v6, 16, v6
	v_and_or_b32 v2, v3, s79, v2
	v_and_or_b32 v3, v5, s79, v4
	s_waitcnt lgkmcnt(1)
	v_bfe_u32 v5, v50, 16, 1
	v_and_or_b32 v4, v8, s79, v6
	v_add3_u32 v5, v50, v5, s78
	s_waitcnt lgkmcnt(0)
; #define LAS __attribute__((address_space(3)))
; #define LDS_WAIT() asm volatile("s_waitcnt lgkmcnt(0)" ::: "memory")
; __device__ __forceinline__ unsigned pk2(float lo, float hi) { return f2bf(lo) | (f2bf(hi) << 16); }
; __device__ __forceinline__ void tr_item(const float* W, int K, int N, const float* kscale, bf16* WT, int dst_row0, LAS float* scr, int k0, int n0, int lane) {
;     ...
;     for (int j = 0; j < 4; ++j) { const int n = (lane >> 3) + 8 * j; const LAS float* s = scr + (8 * c) * 33 + n;
;         u32x4 o; o.x = pk2(s[0 * 33], s[1 * 33]); o.y = pk2(s[2 * 33], s[3 * 33]); o.z = pk2(s[4 * 33], s[5 * 33]); o.w = pk2(s[6 * 33], s[7 * 33]);
;         *(u32x4*)(WT + (size_t)(dst_row0 + n) * K + k0 + 8 * c) = o; }
;     LDS_WAIT(); asm volatile("" ::: "memory");
; __device__ __forceinline__ void prologue(const Args& a, LAS unsigned char* lds, int wave, int lane) {
;     ...
;         if (r < I_WIN) {
;             const float* W = a.in[5] + (size_t)l * D * INCOLS; const float* ks = a.in[4] + (size_t)l * D;
;             const int nblk = NPROJ / 32, kb = r / nblk, nb = r % nblk;
;             tr_item(W, D, INCOLS, ks, (bf16*)(wl + WIN_OFF), 32 * nb, scr, 64 * kb, 32 * nb, lane);
	v_bfe_u32 v6, v52, 16, 1
	v_lshrrev_b32_e32 v5, 16, v5
	v_add3_u32 v6, v52, v6, s78
	v_and_or_b32 v5, v6, s79, v5
	v_or_b32_e32 v6, s2, v12
	v_lshlrev_b32_e32 v54, 11, v6
	v_mov_b32_e32 v55, v15
	v_lshl_add_u64 v[54:55], v[18:19], 0, v[54:55]
	global_store_dwordx4 v[54:55], v[2:5], off sc0 sc1
	v_bfe_u32 v6, v53, 16, 1
	v_add3_u32 v6, v53, v6, s78
	v_bfe_u32 v2, v9, 16, 1
	v_add3_u32 v2, v9, v2, s78
	v_bfe_u32 v3, v7, 16, 1
	v_lshrrev_b32_e32 v2, 16, v2
	v_add3_u32 v3, v7, v3, s78
	v_and_or_b32 v2, v3, s79, v2
	v_bfe_u32 v3, v43, 16, 1
	v_add3_u32 v3, v43, v3, s78
	v_bfe_u32 v4, v45, 16, 1
	v_lshrrev_b32_e32 v3, 16, v3
	v_add3_u32 v4, v45, v4, s78
	v_and_or_b32 v3, v4, s79, v3
	v_bfe_u32 v4, v47, 16, 1
	v_add3_u32 v4, v47, v4, s78
	v_bfe_u32 v5, v49, 16, 1
	v_lshrrev_b32_e32 v4, 16, v4
	v_add3_u32 v5, v49, v5, s78
	v_and_or_b32 v4, v5, s79, v4
	v_bfe_u32 v5, v51, 16, 1
	v_add3_u32 v5, v51, v5, s78
	v_lshrrev_b32_e32 v5, 16, v5
	v_and_or_b32 v5, v6, s79, v5
	v_or_b32_e32 v6, s2, v1
	v_lshlrev_b32_e32 v6, 11, v6
	v_mov_b32_e32 v7, v15
	ds_read2_b32 v[8:9], v25 offset0:16 offset1:24
	v_lshl_add_u64 v[6:7], v[18:19], 0, v[6:7]
	global_store_dwordx4 v[6:7], v[2:5], off sc0 sc1
	ds_read2_b32 v[6:7], v25 offset0:49 offset1:57
	ds_read2_b32 v[42:43], v25 offset0:82 offset1:90
	ds_read2_b32 v[44:45], v25 offset0:115 offset1:123
	s_waitcnt lgkmcnt(3)
	v_bfe_u32 v2, v8, 16, 1
	v_add3_u32 v2, v8, v2, s78
	s_waitcnt lgkmcnt(2)
	v_bfe_u32 v3, v6, 16, 1
	ds_read2_b32 v[46:47], v25 offset0:148 offset1:156
	v_lshrrev_b32_e32 v2, 16, v2
	v_add3_u32 v3, v6, v3, s78
	ds_read2_b32 v[48:49], v25 offset0:181 offset1:189
	v_and_or_b32 v2, v3, s79, v2
	s_waitcnt lgkmcnt(3)
	v_bfe_u32 v3, v42, 16, 1
	v_add3_u32 v3, v42, v3, s78
	s_waitcnt lgkmcnt(2)
	v_bfe_u32 v4, v44, 16, 1
	ds_read2_b32 v[50:51], v25 offset0:214 offset1:222
	v_lshrrev_b32_e32 v3, 16, v3
	v_add3_u32 v4, v44, v4, s78
	ds_read2_b32 v[52:53], v25 offset0:247 offset1:255
	v_and_or_b32 v3, v4, s79, v3
	s_waitcnt lgkmcnt(3)
	v_bfe_u32 v4, v46, 16, 1
	v_add3_u32 v4, v46, v4, s78
	s_waitcnt lgkmcnt(2)
	v_bfe_u32 v5, v48, 16, 1
	v_lshrrev_b32_e32 v4, 16, v4
	v_add3_u32 v5, v48, v5, s78
	v_and_or_b32 v4, v5, s79, v4
	s_waitcnt lgkmcnt(1)
	v_bfe_u32 v5, v50, 16, 1
	v_add3_u32 v5, v50, v5, s78
	s_waitcnt lgkmcnt(0)
	v_bfe_u32 v6, v52, 16, 1
	v_lshrrev_b32_e32 v5, 16, v5
	v_add3_u32 v6, v52, v6, s78
	v_and_or_b32 v5, v6, s79, v5
	v_or_b32_e32 v6, s2, v11
	v_lshlrev_b32_e32 v54, 11, v6
	v_mov_b32_e32 v55, v15
	v_lshl_add_u64 v[54:55], v[18:19], 0, v[54:55]
	global_store_dwordx4 v[54:55], v[2:5], off sc0 sc1
	v_bfe_u32 v6, v53, 16, 1
	v_add3_u32 v6, v53, v6, s78
	v_bfe_u32 v2, v9, 16, 1
	v_add3_u32 v2, v9, v2, s78
	v_bfe_u32 v3, v7, 16, 1
	v_lshrrev_b32_e32 v2, 16, v2
	v_add3_u32 v3, v7, v3, s78
	v_and_or_b32 v2, v3, s79, v2
	v_bfe_u32 v3, v43, 16, 1
	v_add3_u32 v3, v43, v3, s78
	v_bfe_u32 v4, v45, 16, 1
	v_lshrrev_b32_e32 v3, 16, v3
	v_add3_u32 v4, v45, v4, s78
	v_and_or_b32 v3, v4, s79, v3
	v_bfe_u32 v4, v47, 16, 1
	v_add3_u32 v4, v47, v4, s78
	v_bfe_u32 v5, v49, 16, 1
	v_lshrrev_b32_e32 v4, 16, v4
	v_add3_u32 v5, v49, v5, s78
	v_and_or_b32 v4, v5, s79, v4
	v_bfe_u32 v5, v51, 16, 1
	v_add3_u32 v5, v51, v5, s78
	v_lshrrev_b32_e32 v5, 16, v5
	v_and_or_b32 v5, v6, s79, v5
	v_or_b32_e32 v6, s2, v20
	v_lshlrev_b32_e32 v6, 11, v6
	v_mov_b32_e32 v7, v15
	v_lshl_add_u64 v[6:7], v[18:19], 0, v[6:7]
	global_store_dwordx4 v[6:7], v[2:5], off sc0 sc1
	s_waitcnt lgkmcnt(0)
	s_mov_b64 s[2:3], 0
.LBB0_20:
	s_andn2_b64 vcc, exec, s[2:3]
	s_cbranch_vccnz .LBB0_54
	s_mul_i32 s2, s68, 0xa10000
	s_mul_hi_i32 s0, s68, 0xa10000
	s_add_u32 s4, s46, s2
	s_addc_u32 s5, s47, s0
	s_add_i32 s0, s86, 0xdf00
	s_and_b32 s2, s0, 0xffff
	s_mul_i32 s2, s2, 0xba2f
	s_lshr_b32 s3, s2, 16
	s_lshr_b32 s2, s2, 22
	s_mulk_i32 s2, 0x58
	s_sub_i32 s0, s0, s2
	s_lshl_b32 s0, s0, 5
	s_and_b32 s0, s0, 0xffe0
	s_and_b32 s88, s3, 0xffc0
	s_lshl_b32 s70, s0, 2
	s_add_u32 s4, s4, s70
	v_or_b32_e32 v2, s0, v10
	s_addc_u32 s5, s5, 0
	v_cmp_gt_u32_e64 s[2:3], s80, v2
	v_lshl_add_u64 v[6:7], s[4:5], 0, v[14:15]
	v_mov_b32_e32 v2, v15
	v_mov_b32_e32 v3, v15
	v_mov_b32_e32 v4, v15
	v_mov_b32_e32 v5, v15
	v_or_b32_e32 v8, s88, v12
	s_and_saveexec_b64 s[4:5], s[2:3]
	s_cbranch_execz .LBB0_23
	v_mul_u32_u24_e32 v2, 0xa10, v8
	v_lshlrev_b32_e32 v2, 2, v2
	v_mov_b32_e32 v3, v15
	v_lshl_add_u64 v[2:3], v[6:7], 0, v[2:3]
	global_load_dwordx4 v[2:5], v[2:3], off nt

; __device__ __forceinline__ void tr_item(const float* W, int K, int N, const float* kscale, bf16* WT, int dst_row0, LAS float* scr, int k0, int n0, int lane) {
;     const int n4 = 4 * (lane & 7); const bool ok = (n0 + n4) < N;
; #pragma unroll
;     for (int i = 0; i < 8; ++i) { const int kk = 8 * i + (lane >> 3); f32x4 v = ok ? *(const f32x4*)(W + (size_t)(k0 + kk) * N + n0 + n4) : (f32x4){0.f, 0.f, 0.f, 0.f}; if (kscale) v = v * kscale[k0 + kk];
;         scr[kk * 33 + n4] = v[0]; scr[kk * 33 + n4 + 1] = v[1]; scr[kk * 33 + n4 + 2] = v[2]; scr[kk * 33 + n4 + 3] = v[3]; }
.LBB0_25:
	s_waitcnt vmcnt(0)
	ds_write2_b32 v26, v2, v3 offset1:1
	ds_write2_b32 v26, v4, v5 offset0:2 offset1:3
	v_mov_b32_e32 v2, v15
	v_mov_b32_e32 v3, v15
	v_mov_b32_e32 v4, v15
	v_mov_b32_e32 v5, v15
	s_and_saveexec_b64 s[72:73], s[2:3]
	s_cbranch_execz .LBB0_27
	v_or_b32_e32 v2, s88, v1
	v_mul_u32_u24_e32 v2, 0xa10, v2
	v_lshlrev_b32_e32 v2, 2, v2
	v_mov_b32_e32 v3, v15
	v_lshl_add_u64 v[2:3], v[6:7], 0, v[2:3]
	global_load_dwordx4 v[2:5], v[2:3], off nt

; __device__ __forceinline__ void tr_item(const float* W, int K, int N, const float* kscale, bf16* WT, int dst_row0, LAS float* scr, int k0, int n0, int lane) {
;     const int n4 = 4 * (lane & 7); const bool ok = (n0 + n4) < N;
; #pragma unroll
;     for (int i = 0; i < 8; ++i) { const int kk = 8 * i + (lane >> 3); f32x4 v = ok ? *(const f32x4*)(W + (size_t)(k0 + kk) * N + n0 + n4) : (f32x4){0.f, 0.f, 0.f, 0.f}; if (kscale) v = v * kscale[k0 + kk];
;         scr[kk * 33 + n4] = v[0]; scr[kk * 33 + n4 + 1] = v[1]; scr[kk * 33 + n4 + 2] = v[2]; scr[kk * 33 + n4 + 3] = v[3]; }
.LBB0_29:
	s_waitcnt vmcnt(0)
	ds_write2_b32 v27, v2, v3 offset1:1
	ds_write2_b32 v28, v4, v5 offset1:1
	v_mov_b32_e32 v2, v15
	v_mov_b32_e32 v3, v15
	v_mov_b32_e32 v4, v15
	v_mov_b32_e32 v5, v15
	s_and_saveexec_b64 s[72:73], s[2:3]
	s_cbranch_execz .LBB0_31
	v_or_b32_e32 v2, s88, v11
	v_mul_u32_u24_e32 v2, 0xa10, v2
	v_lshlrev_b32_e32 v2, 2, v2
	v_mov_b32_e32 v3, v15
	v_lshl_add_u64 v[2:3], v[6:7], 0, v[2:3]
	global_load_dwordx4 v[2:5], v[2:3], off nt

; __device__ __forceinline__ void tr_item(const float* W, int K, int N, const float* kscale, bf16* WT, int dst_row0, LAS float* scr, int k0, int n0, int lane) {
;     const int n4 = 4 * (lane & 7); const bool ok = (n0 + n4) < N;
; #pragma unroll
;     for (int i = 0; i < 8; ++i) { const int kk = 8 * i + (lane >> 3); f32x4 v = ok ? *(const f32x4*)(W + (size_t)(k0 + kk) * N + n0 + n4) : (f32x4){0.f, 0.f, 0.f, 0.f}; if (kscale) v = v * kscale[k0 + kk];
;         scr[kk * 33 + n4] = v[0]; scr[kk * 33 + n4 + 1] = v[1]; scr[kk * 33 + n4 + 2] = v[2]; scr[kk * 33 + n4 + 3] = v[3]; }
.LBB0_33:
	s_waitcnt vmcnt(0)
	ds_write2_b32 v29, v2, v3 offset1:1
	ds_write2_b32 v30, v4, v5 offset1:1
	v_mov_b32_e32 v2, v15
	v_mov_b32_e32 v3, v15
	v_mov_b32_e32 v4, v15
	v_mov_b32_e32 v5, v15
	s_and_saveexec_b64 s[72:73], s[2:3]
	s_cbranch_execz .LBB0_35
	v_or_b32_e32 v2, s88, v20
	v_mul_u32_u24_e32 v2, 0xa10, v2
	v_lshlrev_b32_e32 v2, 2, v2
	v_mov_b32_e32 v3, v15
	v_lshl_add_u64 v[2:3], v[6:7], 0, v[2:3]
	global_load_dwordx4 v[2:5], v[2:3], off nt

; __device__ __forceinline__ void tr_item(const float* W, int K, int N, const float* kscale, bf16* WT, int dst_row0, LAS float* scr, int k0, int n0, int lane) {
;     const int n4 = 4 * (lane & 7); const bool ok = (n0 + n4) < N;
; #pragma unroll
;     for (int i = 0; i < 8; ++i) { const int kk = 8 * i + (lane >> 3); f32x4 v = ok ? *(const f32x4*)(W + (size_t)(k0 + kk) * N + n0 + n4) : (f32x4){0.f, 0.f, 0.f, 0.f}; if (kscale) v = v * kscale[k0 + kk];
;         scr[kk * 33 + n4] = v[0]; scr[kk * 33 + n4 + 1] = v[1]; scr[kk * 33 + n4 + 2] = v[2]; scr[kk * 33 + n4 + 3] = v[3]; }
.LBB0_37:
	s_waitcnt vmcnt(0)
	ds_write2_b32 v31, v2, v3 offset1:1
	ds_write2_b32 v32, v4, v5 offset1:1
	v_mov_b32_e32 v2, v15
	v_mov_b32_e32 v3, v15
	v_mov_b32_e32 v4, v15
	v_mov_b32_e32 v5, v15
	s_and_saveexec_b64 s[72:73], s[2:3]
	s_cbranch_execz .LBB0_39
	v_or_b32_e32 v2, s88, v21
	v_mul_u32_u24_e32 v2, 0xa10, v2
	v_lshlrev_b32_e32 v2, 2, v2
	v_mov_b32_e32 v3, v15
	v_lshl_add_u64 v[2:3], v[6:7], 0, v[2:3]
	global_load_dwordx4 v[2:5], v[2:3], off nt

; __device__ __forceinline__ void tr_item(const float* W, int K, int N, const float* kscale, bf16* WT, int dst_row0, LAS float* scr, int k0, int n0, int lane) {
;     const int n4 = 4 * (lane & 7); const bool ok = (n0 + n4) < N;
; #pragma unroll
;     for (int i = 0; i < 8; ++i) { const int kk = 8 * i + (lane >> 3); f32x4 v = ok ? *(const f32x4*)(W + (size_t)(k0 + kk) * N + n0 + n4) : (f32x4){0.f, 0.f, 0.f, 0.f}; if (kscale) v = v * kscale[k0 + kk];
;         scr[kk * 33 + n4] = v[0]; scr[kk * 33 + n4 + 1] = v[1]; scr[kk * 33 + n4 + 2] = v[2]; scr[kk * 33 + n4 + 3] = v[3]; }
.LBB0_41:
	s_waitcnt vmcnt(0)
	ds_write2_b32 v33, v2, v3 offset1:1
	ds_write2_b32 v34, v4, v5 offset1:1
	v_mov_b32_e32 v2, v15
	v_mov_b32_e32 v3, v15
	v_mov_b32_e32 v4, v15
	v_mov_b32_e32 v5, v15
	s_and_saveexec_b64 s[72:73], s[2:3]
	s_cbranch_execz .LBB0_43
	v_or_b32_e32 v2, s88, v22
	v_mul_u32_u24_e32 v2, 0xa10, v2
	v_lshlrev_b32_e32 v2, 2, v2
	v_mov_b32_e32 v3, v15
	v_lshl_add_u64 v[2:3], v[6:7], 0, v[2:3]
	global_load_dwordx4 v[2:5], v[2:3], off nt

; __device__ __forceinline__ void tr_item(const float* W, int K, int N, const float* kscale, bf16* WT, int dst_row0, LAS float* scr, int k0, int n0, int lane) {
;     const int n4 = 4 * (lane & 7); const bool ok = (n0 + n4) < N;
; #pragma unroll
;     for (int i = 0; i < 8; ++i) { const int kk = 8 * i + (lane >> 3); f32x4 v = ok ? *(const f32x4*)(W + (size_t)(k0 + kk) * N + n0 + n4) : (f32x4){0.f, 0.f, 0.f, 0.f}; if (kscale) v = v * kscale[k0 + kk];
;         scr[kk * 33 + n4] = v[0]; scr[kk * 33 + n4 + 1] = v[1]; scr[kk * 33 + n4 + 2] = v[2]; scr[kk * 33 + n4 + 3] = v[3]; }
.LBB0_45:
	s_waitcnt vmcnt(0)
	ds_write2_b32 v35, v2, v3 offset1:1
	ds_write2_b32 v36, v4, v5 offset1:1
	v_mov_b32_e32 v2, v15
	v_mov_b32_e32 v3, v15
	v_mov_b32_e32 v4, v15
	v_mov_b32_e32 v5, v15
	s_and_saveexec_b64 s[72:73], s[2:3]
	s_cbranch_execz .LBB0_47
	v_or_b32_e32 v2, s88, v23
	v_mul_u32_u24_e32 v2, 0xa10, v2
	v_lshlrev_b32_e32 v2, 2, v2
	v_mov_b32_e32 v3, v15
	v_lshl_add_u64 v[2:3], v[6:7], 0, v[2:3]
	global_load_dwordx4 v[2:5], v[2:3], off nt

; __device__ __forceinline__ void tr_item(const float* W, int K, int N, const float* kscale, bf16* WT, int dst_row0, LAS float* scr, int k0, int n0, int lane) {
;     const int n4 = 4 * (lane & 7); const bool ok = (n0 + n4) < N;
; #pragma unroll
;     for (int i = 0; i < 8; ++i) { const int kk = 8 * i + (lane >> 3); f32x4 v = ok ? *(const f32x4*)(W + (size_t)(k0 + kk) * N + n0 + n4) : (f32x4){0.f, 0.f, 0.f, 0.f}; if (kscale) v = v * kscale[k0 + kk];
;         scr[kk * 33 + n4] = v[0]; scr[kk * 33 + n4 + 1] = v[1]; scr[kk * 33 + n4 + 2] = v[2]; scr[kk * 33 + n4 + 3] = v[3]; }
.LBB0_49:
	s_waitcnt vmcnt(0)
	ds_write2_b32 v37, v2, v3 offset1:1
	ds_write2_b32 v38, v4, v5 offset1:1
	v_mov_b32_e32 v2, v15
	v_mov_b32_e32 v3, v15
	v_mov_b32_e32 v4, v15
	v_mov_b32_e32 v5, v15
	s_and_saveexec_b64 s[72:73], s[2:3]
	s_cbranch_execz .LBB0_51
	v_or_b32_e32 v2, s88, v24
	v_mul_u32_u24_e32 v2, 0xa10, v2
	v_lshlrev_b32_e32 v2, 2, v2
	v_mov_b32_e32 v3, v15
	v_lshl_add_u64 v[2:3], v[6:7], 0, v[2:3]
	global_load_dwordx4 v[2:5], v[2:3], off nt

; #define LAS __attribute__((address_space(3)))
; #define LDS_WAIT() asm volatile("s_waitcnt lgkmcnt(0)" ::: "memory")
; __device__ __forceinline__ unsigned pk2(float lo, float hi) { return f2bf(lo) | (f2bf(hi) << 16); }
; __device__ __forceinline__ void tr_item(const float* W, int K, int N, const float* kscale, bf16* WT, int dst_row0, LAS float* scr, int k0, int n0, int lane) {
;     const int n4 = 4 * (lane & 7); const bool ok = (n0 + n4) < N;
; #pragma unroll
;     for (int i = 0; i < 8; ++i) { const int kk = 8 * i + (lane >> 3); f32x4 v = ok ? *(const f32x4*)(W + (size_t)(k0 + kk) * N + n0 + n4) : (f32x4){0.f, 0.f, 0.f, 0.f}; if (kscale) v = v * kscale[k0 + kk];
;         scr[kk * 33 + n4] = v[0]; scr[kk * 33 + n4 + 1] = v[1]; scr[kk * 33 + n4 + 2] = v[2]; scr[kk * 33 + n4 + 3] = v[3]; }
;     LDS_WAIT(); asm volatile("" ::: "memory");
;     const int c = lane & 7;
; #pragma unroll
;     for (int j = 0; j < 4; ++j) { const int n = (lane >> 3) + 8 * j; const LAS float* s = scr + (8 * c) * 33 + n;
;         u32x4 o; o.x = pk2(s[0 * 33], s[1 * 33]); o.y = pk2(s[2 * 33], s[3 * 33]); o.z = pk2(s[4 * 33], s[5 * 33]); o.w = pk2(s[6 * 33], s[7 * 33]);
; __device__ __forceinline__ void prologue(const Args& a, LAS unsigned char* lds, int wave, int lane) {
;     ...
;         if (r < 2 * I_W2) {
;             const bool second = r >= I_W2; if (second) r -= I_W2;
;             const float* W = a.in[second ? 15 : 3] + (size_t)l * DFF * D;
;             const int nblk = D / 32, kb = r / nblk, nb = r % nblk;
;             tr_item(W, DFF, D, nullptr, (bf16*)(wl + (second ? W4_OFF : W2_OFF)), 32 * nb, scr, 64 * kb, 32 * nb, lane);
.LBB0_55:
	s_andn2_b64 vcc, exec, s[2:3]
	s_cbranch_vccnz .LBB0_57
	s_cmpk_gt_u32 s86, 0x1b7f
	s_cselect_b64 s[2:3], -1, 0
	s_and_b64 s[4:5], s[2:3], exec
	s_cselect_b32 s4, s82, 0xffffea00
	s_cselect_b32 s0, s81, 0xb00000
	s_add_i32 s4, s4, s83
	s_add_i32 s4, s4, s87
	s_and_b64 s[2:3], s[2:3], exec
	s_cselect_b32 s3, s26, s42
	s_mul_i32 s70, s68, 0xb00000
	s_cselect_b32 s2, s27, s43
	s_mul_hi_i32 s5, s68, 0xb00000
	s_add_u32 s3, s3, s70
	s_addc_u32 s5, s2, s5
	s_add_u32 s70, s84, s0
	s_addc_u32 s71, s85, 0
	s_lshl_b32 s0, s4, 5
	s_and_b32 s0, s0, 0x3e0
	s_lshl_b32 s2, s4, 1
	s_and_b32 s4, s2, 0x7fffffc0
	s_lshl_b32 s2, s0, 2
	s_add_u32 s2, s3, s2
	s_addc_u32 s3, s5, 0
	v_or_b32_e32 v2, s4, v12
	v_mov_b32_e32 v3, v15
	v_or_b32_e32 v4, s4, v1
	v_mov_b32_e32 v5, v15
	v_or_b32_e32 v42, s4, v11
	v_mov_b32_e32 v43, v15
	v_or_b32_e32 v44, s4, v20
	v_mov_b32_e32 v45, v15
	v_or_b32_e32 v50, s4, v21
	v_mov_b32_e32 v51, v15
	v_or_b32_e32 v52, s4, v22
	v_mov_b32_e32 v53, v15
	v_lshl_add_u64 v[18:19], s[2:3], 0, v[14:15]
	v_lshlrev_b64 v[2:3], 12, v[2:3]
	v_lshlrev_b64 v[4:5], 12, v[4:5]
	v_lshlrev_b64 v[42:43], 12, v[42:43]
	v_lshlrev_b64 v[44:45], 12, v[44:45]
	v_lshlrev_b64 v[50:51], 12, v[50:51]
	v_lshlrev_b64 v[52:53], 12, v[52:53]
	v_lshl_add_u64 v[2:3], v[18:19], 0, v[2:3]
	v_lshl_add_u64 v[6:7], v[18:19], 0, v[4:5]
	v_lshl_add_u64 v[42:43], v[18:19], 0, v[42:43]
	v_lshl_add_u64 v[46:47], v[18:19], 0, v[44:45]
	v_lshl_add_u64 v[50:51], v[18:19], 0, v[50:51]
	v_lshl_add_u64 v[54:55], v[18:19], 0, v[52:53]
	global_load_dwordx4 v[2:5], v[2:3], off nt
	s_nop 0
	global_load_dwordx4 v[6:9], v[6:7], off nt
	s_nop 0
	global_load_dwordx4 v[42:45], v[42:43], off nt
	s_nop 0
	global_load_dwordx4 v[46:49], v[46:47], off nt
	s_nop 0
	global_load_dwordx4 v[50:53], v[50:51], off nt
	s_nop 0
	global_load_dwordx4 v[54:57], v[54:55], off nt
	v_or_b32_e32 v58, s4, v23
	v_mov_b32_e32 v59, v15
	v_lshlrev_b64 v[58:59], 12, v[58:59]
	v_lshl_add_u64 v[58:59], v[18:19], 0, v[58:59]
	v_or_b32_e32 v62, s4, v24
	v_mov_b32_e32 v63, v15
	global_load_dwordx4 v[58:61], v[58:59], off nt
	v_lshlrev_b64 v[62:63], 12, v[62:63]
	v_lshl_add_u64 v[18:19], v[18:19], 0, v[62:63]
	global_load_dwordx4 v[62:65], v[18:19], off nt
	s_lshl_b32 s2, s4, 1
	s_add_u32 s2, s70, s2
	v_mov_b32_e32 v17, v15
	s_addc_u32 s3, s71, 0
	v_lshl_add_u64 v[18:19], s[2:3], 0, v[16:17]
	s_waitcnt vmcnt(7)
	ds_write2_b32 v26, v2, v3 offset1:1
	ds_write2_b32 v26, v4, v5 offset0:2 offset1:3
	s_waitcnt vmcnt(6)
	ds_write2_b32 v27, v6, v7 offset1:1
	ds_write2_b32 v28, v8, v9 offset1:1
	s_waitcnt vmcnt(5)
	ds_write2_b32 v29, v42, v43 offset1:1
	ds_write2_b32 v30, v44, v45 offset1:1
	s_waitcnt vmcnt(4)
	ds_write2_b32 v31, v46, v47 offset1:1
	ds_write2_b32 v32, v48, v49 offset1:1
	s_waitcnt vmcnt(3)
	ds_write2_b32 v33, v50, v51 offset1:1
	ds_write2_b32 v34, v52, v53 offset1:1
	s_waitcnt vmcnt(2)
	ds_write2_b32 v35, v54, v55 offset1:1
	ds_write2_b32 v36, v56, v57 offset1:1
	s_waitcnt vmcnt(1)
	ds_write2_b32 v37, v58, v59 offset1:1
	ds_write2_b32 v38, v60, v61 offset1:1
	s_waitcnt vmcnt(0)
	ds_write2_b32 v39, v62, v63 offset1:1
	ds_write2_b32 v40, v64, v65 offset1:1
	s_waitcnt lgkmcnt(0)
	ds_read2_b32 v[6:7], v25 offset0:33 offset1:41
	ds_read2_b32 v[8:9], v25 offset1:8
	ds_read2_b32 v[42:43], v25 offset0:66 offset1:74
	ds_read2_b32 v[44:45], v25 offset0:99 offset1:107
	ds_read2_b32 v[46:47], v25 offset0:132 offset1:140
	ds_read2_b32 v[48:49], v25 offset0:165 offset1:173
	ds_read2_b32 v[50:51], v25 offset0:198 offset1:206
	ds_read2_b32 v[52:53], v25 offset0:231 offset1:239
	s_waitcnt lgkmcnt(6)
	v_bfe_u32 v2, v8, 16, 1
	s_waitcnt lgkmcnt(5)
	v_bfe_u32 v4, v42, 16, 1
	v_bfe_u32 v3, v6, 16, 1
	s_waitcnt lgkmcnt(4)
	v_bfe_u32 v5, v44, 16, 1
	s_waitcnt lgkmcnt(3)
	v_bfe_u32 v17, v46, 16, 1
	v_add3_u32 v2, v8, v2, s78
	v_add3_u32 v4, v42, v4, s78
	s_waitcnt lgkmcnt(2)
; #define LAS __attribute__((address_space(3)))
; #define LDS_WAIT() asm volatile("s_waitcnt lgkmcnt(0)" ::: "memory")
; __device__ __forceinline__ unsigned pk2(float lo, float hi) { return f2bf(lo) | (f2bf(hi) << 16); }
; __device__ __forceinline__ void tr_item(const float* W, int K, int N, const float* kscale, bf16* WT, int dst_row0, LAS float* scr, int k0, int n0, int lane) {
;     ...
;     const int c = lane & 7;
; #pragma unroll
;     for (int j = 0; j < 4; ++j) { const int n = (lane >> 3) + 8 * j; const LAS float* s = scr + (8 * c) * 33 + n;
;         u32x4 o; o.x = pk2(s[0 * 33], s[1 * 33]); o.y = pk2(s[2 * 33], s[3 * 33]); o.z = pk2(s[4 * 33], s[5 * 33]); o.w = pk2(s[6 * 33], s[7 * 33]);
;         *(u32x4*)(WT + (size_t)(dst_row0 + n) * K + k0 + 8 * c) = o; }
;     LDS_WAIT(); asm volatile("" ::: "memory");
	v_bfe_u32 v41, v48, 16, 1
	v_add3_u32 v3, v6, v3, s78
	v_add3_u32 v5, v44, v5, s78
	v_add3_u32 v6, v46, v17, s78
	v_lshrrev_b32_e32 v2, 16, v2
	v_lshrrev_b32_e32 v4, 16, v4
	v_lshrrev_b32_e32 v6, 16, v6
	v_and_or_b32 v2, v3, s79, v2
	v_and_or_b32 v3, v5, s79, v4
	v_add3_u32 v4, v48, v41, s78
	s_waitcnt lgkmcnt(1)
	v_bfe_u32 v5, v50, 16, 1
	v_and_or_b32 v4, v4, s79, v6
	v_add3_u32 v5, v50, v5, s78
	s_waitcnt lgkmcnt(0)
	v_bfe_u32 v6, v52, 16, 1
	v_lshrrev_b32_e32 v5, 16, v5
	v_add3_u32 v6, v52, v6, s78
	v_and_or_b32 v5, v6, s79, v5
	v_or_b32_e32 v6, s0, v12
	v_mul_u32_u24_e32 v6, 0xb00, v6
	v_lshlrev_b32_e32 v54, 1, v6
	v_mov_b32_e32 v55, v15
	v_lshl_add_u64 v[54:55], v[18:19], 0, v[54:55]
	global_store_dwordx4 v[54:55], v[2:5], off sc0 sc1
	v_bfe_u32 v6, v53, 16, 1
	v_add3_u32 v6, v53, v6, s78
	v_bfe_u32 v2, v9, 16, 1
	v_add3_u32 v2, v9, v2, s78
	v_bfe_u32 v3, v7, 16, 1
	v_lshrrev_b32_e32 v2, 16, v2
	v_add3_u32 v3, v7, v3, s78
	v_and_or_b32 v2, v3, s79, v2
	v_bfe_u32 v3, v43, 16, 1
	v_add3_u32 v3, v43, v3, s78
	v_bfe_u32 v4, v45, 16, 1
	v_lshrrev_b32_e32 v3, 16, v3
	v_add3_u32 v4, v45, v4, s78
	v_and_or_b32 v3, v4, s79, v3
	v_bfe_u32 v4, v47, 16, 1
	v_add3_u32 v4, v47, v4, s78
	v_bfe_u32 v5, v49, 16, 1
	v_lshrrev_b32_e32 v4, 16, v4
	v_add3_u32 v5, v49, v5, s78
	v_and_or_b32 v4, v5, s79, v4
	v_bfe_u32 v5, v51, 16, 1
	v_add3_u32 v5, v51, v5, s78
	v_lshrrev_b32_e32 v5, 16, v5
	v_and_or_b32 v5, v6, s79, v5
	v_or_b32_e32 v6, s0, v1
	v_mul_u32_u24_e32 v6, 0xb00, v6
	v_lshlrev_b32_e32 v6, 1, v6
	v_mov_b32_e32 v7, v15
	ds_read2_b32 v[8:9], v25 offset0:16 offset1:24
	v_lshl_add_u64 v[6:7], v[18:19], 0, v[6:7]
	global_store_dwordx4 v[6:7], v[2:5], off sc0 sc1
	ds_read2_b32 v[6:7], v25 offset0:49 offset1:57
	ds_read2_b32 v[42:43], v25 offset0:82 offset1:90
	ds_read2_b32 v[44:45], v25 offset0:115 offset1:123
	s_waitcnt lgkmcnt(3)
	v_bfe_u32 v2, v8, 16, 1
	v_add3_u32 v2, v8, v2, s78
	s_waitcnt lgkmcnt(2)
	v_bfe_u32 v3, v6, 16, 1
	ds_read2_b32 v[46:47], v25 offset0:148 offset1:156
	v_lshrrev_b32_e32 v2, 16, v2
	v_add3_u32 v3, v6, v3, s78
	ds_read2_b32 v[48:49], v25 offset0:181 offset1:189
	v_and_or_b32 v2, v3, s79, v2
	s_waitcnt lgkmcnt(3)
	v_bfe_u32 v3, v42, 16, 1
	v_add3_u32 v3, v42, v3, s78
	s_waitcnt lgkmcnt(2)
	v_bfe_u32 v4, v44, 16, 1
	ds_read2_b32 v[50:51], v25 offset0:214 offset1:222
	v_lshrrev_b32_e32 v3, 16, v3
	v_add3_u32 v4, v44, v4, s78
	ds_read2_b32 v[52:53], v25 offset0:247 offset1:255
	v_and_or_b32 v3, v4, s79, v3
	s_waitcnt lgkmcnt(3)
	v_bfe_u32 v4, v46, 16, 1
	v_add3_u32 v4, v46, v4, s78
	s_waitcnt lgkmcnt(2)
	v_bfe_u32 v5, v48, 16, 1
	v_lshrrev_b32_e32 v4, 16, v4
	v_add3_u32 v5, v48, v5, s78
	v_and_or_b32 v4, v5, s79, v4
	s_waitcnt lgkmcnt(1)
	v_bfe_u32 v5, v50, 16, 1
	v_add3_u32 v5, v50, v5, s78
	s_waitcnt lgkmcnt(0)
	v_bfe_u32 v6, v52, 16, 1
	v_lshrrev_b32_e32 v5, 16, v5
	v_add3_u32 v6, v52, v6, s78
	v_and_or_b32 v5, v6, s79, v5
	v_or_b32_e32 v6, s0, v11
	v_mul_u32_u24_e32 v6, 0xb00, v6
	v_lshlrev_b32_e32 v54, 1, v6
	v_mov_b32_e32 v55, v15
	v_lshl_add_u64 v[54:55], v[18:19], 0, v[54:55]
	global_store_dwordx4 v[54:55], v[2:5], off sc0 sc1
	v_bfe_u32 v6, v53, 16, 1
	v_add3_u32 v6, v53, v6, s78
	v_bfe_u32 v2, v9, 16, 1
	v_add3_u32 v2, v9, v2, s78
	v_bfe_u32 v3, v7, 16, 1
	v_lshrrev_b32_e32 v2, 16, v2
	v_add3_u32 v3, v7, v3, s78
	v_and_or_b32 v2, v3, s79, v2
	v_bfe_u32 v3, v43, 16, 1
	v_add3_u32 v3, v43, v3, s78
	v_bfe_u32 v4, v45, 16, 1
	v_lshrrev_b32_e32 v3, 16, v3
	v_add3_u32 v4, v45, v4, s78
	v_and_or_b32 v3, v4, s79, v3
	v_bfe_u32 v4, v47, 16, 1
	v_add3_u32 v4, v47, v4, s78
	v_bfe_u32 v5, v49, 16, 1
	v_lshrrev_b32_e32 v4, 16, v4
	v_add3_u32 v5, v49, v5, s78
	v_and_or_b32 v4, v5, s79, v4
	v_bfe_u32 v5, v51, 16, 1
	v_add3_u32 v5, v51, v5, s78
	v_lshrrev_b32_e32 v5, 16, v5
	v_and_or_b32 v5, v6, s79, v5
	v_or_b32_e32 v6, s0, v20
	v_mul_u32_u24_e32 v6, 0xb00, v6
	v_lshlrev_b32_e32 v6, 1, v6
	v_mov_b32_e32 v7, v15
	v_lshl_add_u64 v[6:7], v[18:19], 0, v[6:7]
	global_store_dwordx4 v[6:7], v[2:5], off sc0 sc1
	s_waitcnt lgkmcnt(0)

; __device__ __forceinline__ void tr_item(const float* W, int K, int N, const float* kscale, bf16* WT, int dst_row0, LAS float* scr, int k0, int n0, int lane) {
;     const int n4 = 4 * (lane & 7); const bool ok = (n0 + n4) < N;
; #pragma unroll
;     for (int i = 0; i < 8; ++i) { const int kk = 8 * i + (lane >> 3); f32x4 v = ok ? *(const f32x4*)(W + (size_t)(k0 + kk) * N + n0 + n4) : (f32x4){0.f, 0.f, 0.f, 0.f}; if (kscale) v = v * kscale[k0 + kk];
;         scr[kk * 33 + n4] = v[0]; scr[kk * 33 + n4 + 1] = v[1]; scr[kk * 33 + n4 + 2] = v[2]; scr[kk * 33 + n4 + 3] = v[3]; }
; __device__ __forceinline__ void prologue(const Args& a, LAS unsigned char* lds, int wave, int lane) {
;     ...
;         if (r < 2 * I_W1) {
;             const bool second = r >= I_W1; if (second) r -= I_W1;
;             const float* W = a.in[second ? 14 : 2] + (size_t)l * D * NFF; const float* ks = a.in[second ? 13 : 1] + (size_t)l * D;
;             const int nblk = NFF / 32, kb = r / nblk, nb = r % nblk, n0 = 32 * nb;
;             const int dst = n0 < DFF ? (n0 / 128) * 256 + (n0 % 128) : ((n0 - DFF) / 128) * 256 + 128 + ((n0 - DFF) % 128);
;             tr_item(W, D, NFF, ks, (bf16*)(wl + (second ? W3_OFF : W1_OFF)), dst, scr, 64 * kb, n0, lane);
.LBB0_63:
	s_and_b64 s[70:71], s[4:5], exec
	s_cselect_b32 s71, s24, s40
	s_mul_i32 s73, s68, 0x1600000
	s_cselect_b32 s70, s25, s41
	s_mul_hi_i32 s72, s68, 0x1600000
	s_add_u32 s88, s71, s73
	s_addc_u32 s89, s70, s72
	s_and_b64 s[70:71], s[4:5], exec
	s_cselect_b32 s87, s23, s39
	s_cselect_b32 s86, s22, s38
	s_lshl_b64 s[68:69], s[68:69], 12
	s_add_u32 s70, s86, s68
	s_sext_i32_i16 s3, s3
	s_addc_u32 s71, s87, s69
	s_lshl_b32 s68, s3, 6
	s_cmp_lg_u64 s[86:87], 0
	s_cselect_b64 s[72:73], -1, 0
	s_ashr_i32 s3, s2, 31
	s_lshl_b64 s[2:3], s[2:3], 2
	s_add_u32 s2, s88, s2
	v_or_b32_e32 v2, s68, v12
	s_addc_u32 s3, s89, s3
	v_mul_i32_i24_e32 v4, 0x1600, v2
	v_lshl_add_u64 v[18:19], s[2:3], 0, v[14:15]
	v_ashrrev_i32_e32 v5, 31, v4
	v_lshl_add_u64 v[4:5], v[4:5], 2, v[18:19]
	global_load_dwordx4 v[6:9], v[4:5], off nt
	s_cmp_eq_u64 s[86:87], 0
	s_cbranch_scc1 .LBB0_65
	v_ashrrev_i32_e32 v3, 31, v2
	v_lshl_add_u64 v[2:3], v[2:3], 2, s[70:71]
	global_load_dword v2, v[2:3], off
	s_waitcnt vmcnt(0)
	v_pk_mul_f32 v[8:9], v[8:9], v[2:3] op_sel_hi:[1,0]
	v_pk_mul_f32 v[6:7], v[6:7], v[2:3] op_sel_hi:[1,0]
.LBB0_65:
	v_or_b32_e32 v2, s68, v1
	v_mul_i32_i24_e32 v2, 0x1600, v2
	v_ashrrev_i32_e32 v3, 31, v2
	v_lshl_add_u64 v[2:3], v[2:3], 2, v[18:19]
	global_load_dwordx4 v[2:5], v[2:3], off nt
	s_waitcnt vmcnt(1)
	ds_write2_b32 v26, v6, v7 offset1:1
	v_cndmask_b32_e64 v6, 0, 1, s[72:73]
	v_cmp_ne_u32_e64 s[2:3], 1, v6
	s_andn2_b64 vcc, exec, s[72:73]
	ds_write2_b32 v26, v8, v9 offset0:2 offset1:3
	s_cbranch_vccnz .LBB0_67
	s_ashr_i32 s69, s68, 31
	v_lshl_add_u64 v[6:7], s[68:69], 0, v[12:13]
	v_lshl_add_u64 v[6:7], v[6:7], 2, s[70:71]
	global_load_dword v6, v[6:7], off offset:32
	s_waitcnt vmcnt(0)
	v_pk_mul_f32 v[4:5], v[4:5], v[6:7] op_sel_hi:[1,0]
	v_pk_mul_f32 v[2:3], v[2:3], v[6:7] op_sel_hi:[1,0]
.LBB0_67:
	v_or_b32_e32 v6, s68, v11
	v_mul_i32_i24_e32 v6, 0x1600, v6
	v_ashrrev_i32_e32 v7, 31, v6
	v_lshl_add_u64 v[6:7], v[6:7], 2, v[18:19]
	global_load_dwordx4 v[6:9], v[6:7], off nt
	s_and_b64 vcc, exec, s[2:3]
	s_waitcnt vmcnt(1)
	ds_write2_b32 v27, v2, v3 offset1:1
	ds_write2_b32 v28, v4, v5 offset1:1
	s_cbranch_vccnz .LBB0_69
	s_ashr_i32 s69, s68, 31
	v_lshl_add_u64 v[2:3], s[68:69], 0, v[12:13]
	v_lshl_add_u64 v[2:3], v[2:3], 2, s[70:71]
	global_load_dword v2, v[2:3], off offset:64
	s_waitcnt vmcnt(0)
	v_pk_mul_f32 v[8:9], v[8:9], v[2:3] op_sel_hi:[1,0]
	v_pk_mul_f32 v[6:7], v[6:7], v[2:3] op_sel_hi:[1,0]
.LBB0_69:
	v_or_b32_e32 v2, s68, v20
	v_mul_i32_i24_e32 v2, 0x1600, v2
	v_ashrrev_i32_e32 v3, 31, v2
	v_lshl_add_u64 v[2:3], v[2:3], 2, v[18:19]
	global_load_dwordx4 v[2:5], v[2:3], off nt
	s_and_b64 vcc, exec, s[2:3]
	s_waitcnt vmcnt(1)
	ds_write2_b32 v29, v6, v7 offset1:1
	ds_write2_b32 v30, v8, v9 offset1:1
	s_cbranch_vccnz .LBB0_71
	s_ashr_i32 s69, s68, 31
	v_lshl_add_u64 v[6:7], s[68:69], 0, v[12:13]
	v_lshl_add_u64 v[6:7], v[6:7], 2, s[70:71]
	global_load_dword v6, v[6:7], off offset:96
	s_waitcnt vmcnt(0)
	v_pk_mul_f32 v[4:5], v[4:5], v[6:7] op_sel_hi:[1,0]
	v_pk_mul_f32 v[2:3], v[2:3], v[6:7] op_sel_hi:[1,0]
.LBB0_71:
	v_or_b32_e32 v6, s68, v21
	v_mul_i32_i24_e32 v6, 0x1600, v6
	v_ashrrev_i32_e32 v7, 31, v6
	v_lshl_add_u64 v[6:7], v[6:7], 2, v[18:19]
	global_load_dwordx4 v[6:9], v[6:7], off nt
	s_and_b64 vcc, exec, s[2:3]
	s_waitcnt vmcnt(1)
	ds_write2_b32 v31, v2, v3 offset1:1
	ds_write2_b32 v32, v4, v5 offset1:1
	s_cbranch_vccnz .LBB0_73
	s_ashr_i32 s69, s68, 31
	v_lshl_add_u64 v[2:3], s[68:69], 0, v[12:13]
	v_lshl_add_u64 v[2:3], v[2:3], 2, s[70:71]
	global_load_dword v2, v[2:3], off offset:128
	s_waitcnt vmcnt(0)
	v_pk_mul_f32 v[8:9], v[8:9], v[2:3] op_sel_hi:[1,0]
	v_pk_mul_f32 v[6:7], v[6:7], v[2:3] op_sel_hi:[1,0]
.LBB0_73:
	v_or_b32_e32 v2, s68, v22
	v_mul_i32_i24_e32 v2, 0x1600, v2
	v_ashrrev_i32_e32 v3, 31, v2
	v_lshl_add_u64 v[2:3], v[2:3], 2, v[18:19]
	global_load_dwordx4 v[2:5], v[2:3], off nt
	s_and_b64 vcc, exec, s[2:3]
	s_waitcnt vmcnt(1)
	ds_write2_b32 v33, v6, v7 offset1:1
	ds_write2_b32 v34, v8, v9 offset1:1
	s_cbranch_vccnz .LBB0_75
	s_ashr_i32 s69, s68, 31
	v_lshl_add_u64 v[6:7], s[68:69], 0, v[12:13]
	v_lshl_add_u64 v[6:7], v[6:7], 2, s[70:71]
	global_load_dword v6, v[6:7], off offset:160
	s_waitcnt vmcnt(0)
	v_pk_mul_f32 v[4:5], v[4:5], v[6:7] op_sel_hi:[1,0]
	v_pk_mul_f32 v[2:3], v[2:3], v[6:7] op_sel_hi:[1,0]
.LBB0_75:
	v_or_b32_e32 v6, s68, v23
	v_mul_i32_i24_e32 v6, 0x1600, v6
	v_ashrrev_i32_e32 v7, 31, v6
	v_lshl_add_u64 v[6:7], v[6:7], 2, v[18:19]
	global_load_dwordx4 v[6:9], v[6:7], off nt
	s_and_b64 vcc, exec, s[2:3]
	s_waitcnt vmcnt(1)
	ds_write2_b32 v35, v2, v3 offset1:1
	ds_write2_b32 v36, v4, v5 offset1:1
	s_cbranch_vccnz .LBB0_77
	s_ashr_i32 s69, s68, 31
	v_lshl_add_u64 v[2:3], s[68:69], 0, v[12:13]
	v_lshl_add_u64 v[2:3], v[2:3], 2, s[70:71]
	global_load_dword v2, v[2:3], off offset:192
	s_waitcnt vmcnt(0)
	v_pk_mul_f32 v[8:9], v[8:9], v[2:3] op_sel_hi:[1,0]
	v_pk_mul_f32 v[6:7], v[6:7], v[2:3] op_sel_hi:[1,0]
.LBB0_77:
	v_or_b32_e32 v2, s68, v24
	v_mul_i32_i24_e32 v2, 0x1600, v2
	v_ashrrev_i32_e32 v3, 31, v2
	v_lshl_add_u64 v[2:3], v[2:3], 2, v[18:19]
	global_load_dwordx4 v[2:5], v[2:3], off nt
	s_and_b64 vcc, exec, s[72:73]
	s_waitcnt vmcnt(1)
	ds_write2_b32 v37, v6, v7 offset1:1
	ds_write2_b32 v38, v8, v9 offset1:1
	s_cbranch_vccz .LBB0_79
	s_ashr_i32 s69, s68, 31
	v_lshl_add_u64 v[6:7], s[68:69], 0, v[12:13]
	v_lshl_add_u64 v[6:7], v[6:7], 2, s[70:71]
	global_load_dword v6, v[6:7], off offset:224
	s_waitcnt vmcnt(0)
	v_pk_mul_f32 v[8:9], v[4:5], v[6:7] op_sel_hi:[1,0]
	v_pk_mul_f32 v[6:7], v[2:3], v[6:7] op_sel_hi:[1,0]
	s_cbranch_execnz .LBB0_14
	s_branch .LBB0_80

; __device__ __forceinline__ u64 ss_fix(float s) { return (u64)(s * 1099511627776.0f); }
; __device__ __forceinline__ void prologue(const Args& a, LAS unsigned char* lds, int wave, int lane) {
;     ...
;       for (int m = 2 * gw; m < M; m += 2 * NGW) {
;           const f32x4* xr = (const f32x4*)(x + (size_t)m * D) + lane; f32x4 v[2][4]; float s[2] = {0.f, 0.f};
; #pragma unroll
;           for (int r = 0; r < 2; ++r)
; #pragma unroll
;               for (int j = 0; j < 4; ++j) v[r][j] = xr[r * (D / 4) + 64 * j];
; #pragma unroll
;           for (int r = 0; r < 2; ++r) {
; #pragma unroll
;               for (int j = 0; j < 4; ++j) s[r] += (v[r][j][0] * v[r][j][0] + v[r][j][1] * v[r][j][1]) + (v[r][j][2] * v[r][j][2] + v[r][j][3] * v[r][j][3]);
;               s[r] = wave_sum(s[r]); if (lane == 0) rs0[m + r] = ss_fix(s[r]);
.LBB0_92:
	global_load_dwordx4 v[30:33], v[38:39], off offset:-4096 nt
	global_load_dwordx4 v[26:29], v[38:39], off offset:-3072 nt
	s_waitcnt lgkmcnt(0)
	global_load_dwordx4 v[22:25], v[38:39], off offset:-2048 nt
	global_load_dwordx4 v[18:21], v[38:39], off offset:-1024 nt
	global_load_dwordx4 v[14:17], v[38:39], off nt
	global_load_dwordx4 v[10:13], v[38:39], off offset:1024 nt
	global_load_dwordx4 v[6:9], v[38:39], off offset:2048 nt
	global_load_dwordx4 v[2:5], v[38:39], off offset:3072 nt
	s_waitcnt vmcnt(7)
	v_mul_f32_e32 v46, v31, v31
	v_mul_f32_e32 v47, v33, v33
	s_waitcnt vmcnt(6)
	v_mul_f32_e32 v48, v27, v27
	v_mul_f32_e32 v49, v29, v29
	s_waitcnt vmcnt(5)
	v_mul_f32_e32 v50, v23, v23
	v_mul_f32_e32 v51, v25, v25
	v_fmac_f32_e32 v46, v30, v30
	v_fmac_f32_e32 v47, v32, v32
	v_fmac_f32_e32 v48, v26, v26
	v_fmac_f32_e32 v49, v28, v28
	s_waitcnt vmcnt(4)
	v_mul_f32_e32 v52, v19, v19
	v_mul_f32_e32 v53, v21, v21
	v_fmac_f32_e32 v50, v22, v22
	v_fmac_f32_e32 v51, v24, v24
	v_add_f32_e32 v46, v46, v47
	v_add_f32_e32 v47, v48, v49
	v_fmac_f32_e32 v52, v18, v18
	v_fmac_f32_e32 v53, v20, v20
	v_add_f32_e32 v48, v50, v51
	v_add_f32_e32 v46, v46, v47
	v_add_f32_e32 v46, v46, v48
	v_add_f32_e32 v47, v52, v53
	v_add_f32_e32 v46, v46, v47
	ds_bpermute_b32 v47, v1, v46
	s_waitcnt lgkmcnt(0)
	v_add_f32_e32 v46, v46, v47
	ds_bpermute_b32 v47, v40, v46
	s_waitcnt lgkmcnt(0)
	v_add_f32_e32 v46, v46, v47
	ds_bpermute_b32 v47, v41, v46
	s_waitcnt lgkmcnt(0)
	v_add_f32_e32 v46, v46, v47
	ds_bpermute_b32 v47, v42, v46
	s_waitcnt lgkmcnt(0)
	v_add_f32_e32 v46, v46, v47
	ds_bpermute_b32 v47, v43, v46
	s_waitcnt lgkmcnt(0)
	v_add_f32_e32 v46, v46, v47
	ds_bpermute_b32 v47, v44, v46
	s_and_saveexec_b64 s[40:41], s[2:3]
	s_cbranch_execz .LBB0_94
	s_waitcnt lgkmcnt(0)
	v_add_f32_e32 v46, v46, v47
	v_mul_f32_e32 v46, 0x53800000, v46
	v_trunc_f32_e32 v46, v46
	v_mul_f32_e32 v47, 0x2f800000, v46
	v_floor_f32_e32 v47, v47
	v_fmac_f32_e32 v46, 0xcf800000, v47
	v_cvt_u32_f32_e32 v46, v46
	v_cvt_u32_f32_e32 v47, v47
	s_add_u32 s30, s34, s22
	s_addc_u32 s31, s35, s23
	global_store_dwordx2 v45, v[46:47], s[30:31] sc0 sc1

; __global__ void __launch_bounds__(NTHREADS, 2) fwd(Args a) {
;     ...
;     if (IN(NPHASE - 1)) {
;         const int gw = r * NWAVES + wave, NGW = GS * NWAVES; const size_t tb = (size_t)b * SEQ;
;         const float* fw = a.in[16]; const u64* rs6 = (const u64*)(a.ws + WS_ROWSS) + (size_t)6 * M + tb; const bf16* XN = (const bf16*)(a.ws + WS_XN) + tb * D; float* outb = a.out + tb * D;
;         f32x4 wv[2][2];
; #pragma unroll
;         for (int j = 0; j < 2; ++j) { wv[j][0] = *((const f32x4*)fw + 2 * (lane + 64 * j)); wv[j][1] = *((const f32x4*)fw + 2 * (lane + 64 * j) + 1); }
;         for (int m = gw; m < SEQ; m += 2 * NGW) {
;             const int m1 = m + NGW; const bool two = m1 < SEQ;
;             u32x4 xv[2][2]; u64 sv[2];
;             sv[0] = rs6[m]; sv[1] = two ? rs6[m1] : sv[0];
; #pragma unroll
;             for (int j = 0; j < 2; ++j) { xv[0][j] = *((const u32x4*)(XN + (size_t)m * D) + lane + 64 * j); xv[1][j] = two ? *((const u32x4*)(XN + (size_t)m1 * D) + lane + 64 * j) : xv[0][j]; }
;             asm volatile("" : "+v"(xv[0][0]), "+v"(xv[0][1]), "+v"(xv[1][0]), "+v"(xv[1][1]), "+v"(sv[0]), "+v"(sv[1]) :: "memory");
.LBB0_1431:
	s_cmp_gt_i32 s52, 19
	s_cselect_b64 s[0:1], -1, 0
	s_xor_b64 s[2:3], s[2:3], -1
	s_or_b64 s[0:1], s[0:1], s[2:3]
	s_and_b64 vcc, exec, s[0:1]
	s_cbranch_vccnz .LBB0_1445
	s_cmpk_gt_i32 s38, 0xfff
	s_cbranch_scc1 .LBB0_1445
	v_readlane_b32 s6, v230, 0
	v_readlane_b32 s7, v230, 1
	v_readlane_b32 s4, v230, 2
	v_readlane_b32 s5, v230, 3
	v_readlane_b32 s0, v230, 6
	v_readlane_b32 s1, v230, 7
	s_waitcnt lgkmcnt(0)
	s_nop 4
	s_add_u32 s0, s34, s0
	s_addc_u32 s1, s35, s1
	s_add_u32 s12, s0, 0x280000
	s_addc_u32 s13, s1, 0
	s_lshl_b64 s[0:1], s[40:41], 2
	s_add_u32 s4, s4, s0
	s_addc_u32 s5, s5, s1
	v_mov_b32_e32 v1, 0
	v_lshlrev_b32_e32 v2, 3, v200
	v_lshlrev_b32_e32 v3, 4, v200
	v_mov_b32_e32 v4, 0x358637bd
	v_mov_b32_e32 v65, 0
	global_load_dwordx4 v[8:11], v3, s[6:7] offset:0
	global_load_dwordx4 v[12:15], v3, s[6:7] offset:1024
	global_load_dwordx4 v[16:19], v3, s[6:7] offset:2048
	global_load_dwordx4 v[20:23], v3, s[6:7] offset:3072
	s_waitcnt vmcnt(0)
	s_lshl_b32 s14, s38, 11
	s_add_u32 s14, s22, s14
	s_addc_u32 s15, s23, 0
	s_lshl_b32 s16, s38, 3
	s_add_u32 s16, s12, s16
	s_addc_u32 s17, s13, 0
	global_load_dwordx2 v[24:25], v1, s[16:17] nt
	global_load_dwordx2 v[26:27], v2, s[14:15] offset:0 nt
	global_load_dwordx2 v[28:29], v2, s[14:15] offset:512 nt
	global_load_dwordx2 v[30:31], v2, s[14:15] offset:1024 nt
	global_load_dwordx2 v[32:33], v2, s[14:15] offset:1536 nt
	s_add_u32 s20, s38, s36
	s_cmp_lt_u32 s20, 0x1000
	s_cbranch_scc0 .Lfn_a
	s_lshl_b32 s14, s20, 11
	s_add_u32 s14, s22, s14
	s_addc_u32 s15, s23, 0
	s_lshl_b32 s16, s20, 3
	s_add_u32 s16, s12, s16
	s_addc_u32 s17, s13, 0
	global_load_dwordx2 v[36:37], v1, s[16:17] nt
	global_load_dwordx2 v[38:39], v2, s[14:15] offset:0 nt
	global_load_dwordx2 v[40:41], v2, s[14:15] offset:512 nt
	global_load_dwordx2 v[42:43], v2, s[14:15] offset:1024 nt
	global_load_dwordx2 v[44:45], v2, s[14:15] offset:1536 nt
.Lfn_a:
	s_lshl_b32 s20, s36, 1
	s_add_u32 s20, s38, s20
	s_cmp_lt_u32 s20, 0x1000
	s_cbranch_scc0 .Lfn_a_t
	s_lshl_b32 s14, s20, 11
	s_add_u32 s14, s22, s14
	s_addc_u32 s15, s23, 0
	s_lshl_b32 s16, s20, 3
	s_add_u32 s16, s12, s16
	s_addc_u32 s17, s13, 0
	global_load_dwordx2 v[48:49], v1, s[16:17] nt
	global_load_dwordx2 v[50:51], v2, s[14:15] offset:0 nt
	global_load_dwordx2 v[52:53], v2, s[14:15] offset:512 nt
	global_load_dwordx2 v[54:55], v2, s[14:15] offset:1024 nt
	global_load_dwordx2 v[56:57], v2, s[14:15] offset:1536 nt
	s_waitcnt vmcnt(10)
	s_branch .Lfn_a_p

; __global__ void __launch_bounds__(NTHREADS, 2) fwd(Args a) {
;     ...
;         for (int m = gw; m < SEQ; m += 2 * NGW) {
;             const int m1 = m + NGW; const bool two = m1 < SEQ;
;             u32x4 xv[2][2]; u64 sv[2];
;             sv[0] = rs6[m]; sv[1] = two ? rs6[m1] : sv[0];
; #pragma unroll
;             for (int j = 0; j < 2; ++j) { xv[0][j] = *((const u32x4*)(XN + (size_t)m * D) + lane + 64 * j); xv[1][j] = two ? *((const u32x4*)(XN + (size_t)m1 * D) + lane + 64 * j) : xv[0][j]; }
;             asm volatile("" : "+v"(xv[0][0]), "+v"(xv[0][1]), "+v"(xv[1][0]), "+v"(xv[1][1]), "+v"(sv[0]), "+v"(sv[1]) :: "memory");
.Lfn_b:
	s_lshl_b32 s20, s36, 1
	s_add_u32 s20, s38, s20
	s_cmp_lt_u32 s20, 0x1000
	s_cbranch_scc0 .Lfn_b_t
	s_lshl_b32 s14, s20, 11
	s_add_u32 s14, s22, s14
	s_addc_u32 s15, s23, 0
	s_lshl_b32 s16, s20, 3
	s_add_u32 s16, s12, s16
	s_addc_u32 s17, s13, 0
	global_load_dwordx2 v[24:25], v1, s[16:17] nt
	global_load_dwordx2 v[26:27], v2, s[14:15] offset:0 nt
	global_load_dwordx2 v[28:29], v2, s[14:15] offset:512 nt
	global_load_dwordx2 v[30:31], v2, s[14:15] offset:1024 nt
	global_load_dwordx2 v[32:33], v2, s[14:15] offset:1536 nt
	s_waitcnt vmcnt(14)
	s_branch .Lfn_b_p

; __global__ void __launch_bounds__(NTHREADS, 2) fwd(Args a) {
;     ...
;         for (int m = gw; m < SEQ; m += 2 * NGW) {
;             const int m1 = m + NGW; const bool two = m1 < SEQ;
;             u32x4 xv[2][2]; u64 sv[2];
;             sv[0] = rs6[m]; sv[1] = two ? rs6[m1] : sv[0];
; #pragma unroll
;             for (int j = 0; j < 2; ++j) { xv[0][j] = *((const u32x4*)(XN + (size_t)m * D) + lane + 64 * j); xv[1][j] = two ? *((const u32x4*)(XN + (size_t)m1 * D) + lane + 64 * j) : xv[0][j]; }
;             asm volatile("" : "+v"(xv[0][0]), "+v"(xv[0][1]), "+v"(xv[1][0]), "+v"(xv[1][1]), "+v"(sv[0]), "+v"(sv[1]) :: "memory");
.Lfn_c:
	s_lshl_b32 s20, s36, 1
	s_add_u32 s20, s38, s20
	s_cmp_lt_u32 s20, 0x1000
	s_cbranch_scc0 .Lfn_c_t
	s_lshl_b32 s14, s20, 11
	s_add_u32 s14, s22, s14
	s_addc_u32 s15, s23, 0
	s_lshl_b32 s16, s20, 3
	s_add_u32 s16, s12, s16
	s_addc_u32 s17, s13, 0
	global_load_dwordx2 v[36:37], v1, s[16:17] nt
	global_load_dwordx2 v[38:39], v2, s[14:15] offset:0 nt
	global_load_dwordx2 v[40:41], v2, s[14:15] offset:512 nt
	global_load_dwordx2 v[42:43], v2, s[14:15] offset:1024 nt
	global_load_dwordx2 v[44:45], v2, s[14:15] offset:1536 nt
	s_waitcnt vmcnt(18)
	s_branch .Lfn_c_p

; __global__ void __launch_bounds__(NTHREADS, 2) fwd(Args a) {
;     ...
;         for (int m = gw; m < SEQ; m += 2 * NGW) {
;             const int m1 = m + NGW; const bool two = m1 < SEQ;
;             u32x4 xv[2][2]; u64 sv[2];
;             sv[0] = rs6[m]; sv[1] = two ? rs6[m1] : sv[0];
; #pragma unroll
;             for (int j = 0; j < 2; ++j) { xv[0][j] = *((const u32x4*)(XN + (size_t)m * D) + lane + 64 * j); xv[1][j] = two ? *((const u32x4*)(XN + (size_t)m1 * D) + lane + 64 * j) : xv[0][j]; }
;             asm volatile("" : "+v"(xv[0][0]), "+v"(xv[0][1]), "+v"(xv[1][0]), "+v"(xv[1][1]), "+v"(sv[0]), "+v"(sv[1]) :: "memory");
.Lfn_d:
	s_lshl_b32 s20, s36, 1
	s_add_u32 s20, s38, s20
	s_cmp_lt_u32 s20, 0x1000
	s_cbranch_scc0 .Lfn_d_t
	s_lshl_b32 s14, s20, 11
	s_add_u32 s14, s22, s14
	s_addc_u32 s15, s23, 0
	s_lshl_b32 s16, s20, 3
	s_add_u32 s16, s12, s16
	s_addc_u32 s17, s13, 0
	global_load_dwordx2 v[48:49], v1, s[16:17] nt
	global_load_dwordx2 v[50:51], v2, s[14:15] offset:0 nt
	global_load_dwordx2 v[52:53], v2, s[14:15] offset:512 nt
	global_load_dwordx2 v[54:55], v2, s[14:15] offset:1024 nt
	global_load_dwordx2 v[56:57], v2, s[14:15] offset:1536 nt
	s_waitcnt vmcnt(18)
	s_branch .Lfn_d_p

; __global__ void __launch_bounds__(NTHREADS, 2) fwd(Args a) {
;     ...
;         for (int m = gw; m < SEQ; m += 2 * NGW) {
;             const int m1 = m + NGW; const bool two = m1 < SEQ;
;             u32x4 xv[2][2]; u64 sv[2];
;             sv[0] = rs6[m]; sv[1] = two ? rs6[m1] : sv[0];
; #pragma unroll
;             for (int j = 0; j < 2; ++j) { xv[0][j] = *((const u32x4*)(XN + (size_t)m * D) + lane + 64 * j); xv[1][j] = two ? *((const u32x4*)(XN + (size_t)m1 * D) + lane + 64 * j) : xv[0][j]; }
;             asm volatile("" : "+v"(xv[0][0]), "+v"(xv[0][1]), "+v"(xv[1][0]), "+v"(xv[1][1]), "+v"(sv[0]), "+v"(sv[1]) :: "memory");
.Lfn_e:
	s_lshl_b32 s20, s36, 1
	s_add_u32 s20, s38, s20
	s_cmp_lt_u32 s20, 0x1000
	s_cbranch_scc0 .Lfn_e_t
	s_lshl_b32 s14, s20, 11
	s_add_u32 s14, s22, s14
	s_addc_u32 s15, s23, 0
	s_lshl_b32 s16, s20, 3
	s_add_u32 s16, s12, s16
	s_addc_u32 s17, s13, 0
	global_load_dwordx2 v[24:25], v1, s[16:17] nt
	global_load_dwordx2 v[26:27], v2, s[14:15] offset:0 nt
	global_load_dwordx2 v[28:29], v2, s[14:15] offset:512 nt
	global_load_dwordx2 v[30:31], v2, s[14:15] offset:1024 nt
	global_load_dwordx2 v[32:33], v2, s[14:15] offset:1536 nt
	s_waitcnt vmcnt(18)
	s_branch .Lfn_e_p
